# phase 0 weight-conversion items: per-item source pointer fetched with s_load instead of a vector load + vmcnt(0) that also waited for the previous item's store
# speedup vs baseline: 1.1588x; 1.0029x over previous
.LBB0_98:
	v_readfirstlane_b32 s98, v8
	v_readfirstlane_b32 s99, v9
	s_nop 3
	s_load_dwordx2 s[98:99], s[98:99], 0x0
	v_lshrrev_b32_e32 v8, 5, v2
	v_cvt_f32_u32_e32 v9, v8
	v_sub_u32_e32 v19, 0, v13
	v_lshrrev_b32_e32 v20, 2, v12
	v_and_b32_e32 v24, 31, v12
	v_rcp_iflag_f32_e32 v9, v9
	v_max_i32_e32 v12, v13, v19
	v_sub_u32_e32 v19, 0, v8
	v_ashrrev_i32_e32 v18, 31, v13
	v_mul_f32_e32 v9, 0x4f7ffffe, v9
	v_cvt_u32_f32_e32 v9, v9
	v_and_b32_e32 v20, 56, v20
	v_lshlrev_b64 v[16:17], 2, v[2:3]
	v_mul_lo_u32 v19, v19, v9
	v_mul_hi_u32 v19, v9, v19
	v_add_u32_e32 v9, v9, v19
	v_mul_hi_u32 v9, v12, v9
	v_mul_lo_u32 v19, v9, v8
	v_sub_u32_e32 v12, v12, v19
	v_add_u32_e32 v21, 1, v9
	v_cmp_ge_u32_e32 vcc, v12, v8
	v_sub_u32_e32 v19, v12, v8
	s_nop 0
	v_cndmask_b32_e32 v9, v9, v21, vcc
	v_cndmask_b32_e32 v12, v12, v19, vcc
	v_add_u32_e32 v19, 1, v9
	v_cmp_ge_u32_e32 vcc, v12, v8
	s_nop 1
	v_cndmask_b32_e32 v9, v9, v19, vcc
	v_xor_b32_e32 v9, v9, v18
	v_sub_u32_e32 v9, v9, v18
	v_mul_lo_u32 v12, v9, v8
	v_lshl_or_b32 v8, v9, 6, v20
	v_sub_u32_e32 v25, v13, v12
	v_mad_u64_u32 v[12:13], s[36:37], v8, v2, 0
	v_ashrrev_i32_e32 v9, 31, v8
	v_mov_b32_e32 v18, v13
	v_mad_u64_u32 v[18:19], s[36:37], v9, v2, v[18:19]
	v_lshl_or_b32 v20, v25, 5, v24
	v_mov_b32_e32 v13, v18
	v_ashrrev_i32_e32 v21, 31, v20
	v_cmp_ne_u64_e32 vcc, 0, v[10:11]
	s_waitcnt lgkmcnt(0)
	v_mov_b32_e32 v14, s98
	v_mov_b32_e32 v15, s99
	v_lshl_add_u64 v[12:13], v[12:13], 2, v[14:15]
	v_lshl_add_u64 v[26:27], v[20:21], 2, v[12:13]
	v_lshl_add_u64 v[28:29], v[26:27], 0, v[16:17]
	v_lshl_add_u64 v[30:31], v[28:29], 0, v[16:17]
	v_lshl_add_u64 v[32:33], v[30:31], 0, v[16:17]
	v_lshl_add_u64 v[34:35], v[32:33], 0, v[16:17]
	v_lshl_add_u64 v[36:37], v[34:35], 0, v[16:17]
	v_lshl_add_u64 v[38:39], v[36:37], 0, v[16:17]
	v_lshl_add_u64 v[40:41], v[38:39], 0, v[16:17]
	global_load_dword v18, v[26:27], off nt
	global_load_dword v19, v[28:29], off nt
	global_load_dword v16, v[30:31], off nt
	global_load_dword v17, v[32:33], off nt
	global_load_dword v14, v[34:35], off nt
	global_load_dword v15, v[36:37], off nt
	global_load_dword v12, v[38:39], off nt
	global_load_dword v13, v[40:41], off nt
	s_and_saveexec_b64 s[36:37], vcc
	s_cbranch_execz .LBB0_100
	v_lshl_add_u64 v[10:11], v[8:9], 2, v[10:11]
	global_load_dwordx4 v[26:29], v[10:11], off
	global_load_dwordx4 v[30:33], v[10:11], off offset:16
	s_waitcnt vmcnt(1)
	v_pk_mul_f32 v[18:19], v[18:19], v[26:27]
	v_pk_mul_f32 v[16:17], v[16:17], v[28:29]
	s_waitcnt vmcnt(0)
	v_pk_mul_f32 v[14:15], v[14:15], v[30:31]
	v_pk_mul_f32 v[12:13], v[12:13], v[32:33]

.LBB0_149:
	v_readfirstlane_b32 s98, v8
	v_readfirstlane_b32 s99, v9
	s_nop 3
	s_load_dwordx2 s[98:99], s[98:99], 0x0
	v_lshrrev_b32_e32 v8, 5, v2
	v_cvt_f32_u32_e32 v9, v8
	v_sub_u32_e32 v19, 0, v13
	v_lshrrev_b32_e32 v20, 2, v12
	v_and_b32_e32 v23, 31, v12
	v_rcp_iflag_f32_e32 v9, v9
	v_max_i32_e32 v12, v13, v19
	v_sub_u32_e32 v19, 0, v8
	v_ashrrev_i32_e32 v18, 31, v13
	v_mul_f32_e32 v9, 0x4f7ffffe, v9
	v_cvt_u32_f32_e32 v9, v9
	v_and_b32_e32 v20, 56, v20
	v_lshlrev_b64 v[16:17], 2, v[2:3]
	v_mul_lo_u32 v19, v19, v9
	v_mul_hi_u32 v19, v9, v19
	v_add_u32_e32 v9, v9, v19
	v_mul_hi_u32 v9, v12, v9
	v_mul_lo_u32 v19, v9, v8
	v_sub_u32_e32 v12, v12, v19
	v_add_u32_e32 v21, 1, v9
	v_cmp_ge_u32_e32 vcc, v12, v8
	v_sub_u32_e32 v19, v12, v8
	s_nop 0
	v_cndmask_b32_e32 v9, v9, v21, vcc
	v_cndmask_b32_e32 v12, v12, v19, vcc
	v_add_u32_e32 v19, 1, v9
	v_cmp_ge_u32_e32 vcc, v12, v8
	s_nop 1
	v_cndmask_b32_e32 v9, v9, v19, vcc
	v_xor_b32_e32 v9, v9, v18
	v_sub_u32_e32 v9, v9, v18
	v_mul_lo_u32 v12, v9, v8
	v_lshl_or_b32 v8, v9, 6, v20
	v_sub_u32_e32 v24, v13, v12
	v_mad_u64_u32 v[12:13], s[38:39], v8, v2, 0
	v_ashrrev_i32_e32 v9, 31, v8
	v_mov_b32_e32 v18, v13
	v_mad_u64_u32 v[18:19], s[38:39], v9, v2, v[18:19]
	v_lshl_or_b32 v20, v24, 5, v23
	v_mov_b32_e32 v13, v18
	v_ashrrev_i32_e32 v21, 31, v20
	v_cmp_ne_u64_e32 vcc, 0, v[10:11]
	s_waitcnt lgkmcnt(0)
	v_mov_b32_e32 v14, s98
	v_mov_b32_e32 v15, s99
	v_lshl_add_u64 v[12:13], v[12:13], 2, v[14:15]
	v_lshl_add_u64 v[26:27], v[20:21], 2, v[12:13]
	v_lshl_add_u64 v[28:29], v[26:27], 0, v[16:17]
	v_lshl_add_u64 v[30:31], v[28:29], 0, v[16:17]
	v_lshl_add_u64 v[32:33], v[30:31], 0, v[16:17]
	v_lshl_add_u64 v[34:35], v[32:33], 0, v[16:17]
	v_lshl_add_u64 v[36:37], v[34:35], 0, v[16:17]
	v_lshl_add_u64 v[38:39], v[36:37], 0, v[16:17]
	v_lshl_add_u64 v[40:41], v[38:39], 0, v[16:17]
	global_load_dword v18, v[26:27], off nt
	global_load_dword v19, v[28:29], off nt
	global_load_dword v16, v[30:31], off nt
	global_load_dword v17, v[32:33], off nt
	global_load_dword v14, v[34:35], off nt
	global_load_dword v15, v[36:37], off nt
	global_load_dword v12, v[38:39], off nt
	global_load_dword v13, v[40:41], off nt
	s_and_saveexec_b64 s[38:39], vcc
	s_cbranch_execz .LBB0_151
	v_lshl_add_u64 v[10:11], v[8:9], 2, v[10:11]
	global_load_dwordx4 v[26:29], v[10:11], off
	global_load_dwordx4 v[30:33], v[10:11], off offset:16
	s_waitcnt vmcnt(1)
	v_pk_mul_f32 v[18:19], v[18:19], v[26:27]
	v_pk_mul_f32 v[16:17], v[16:17], v[28:29]
	s_waitcnt vmcnt(0)
	v_pk_mul_f32 v[14:15], v[14:15], v[30:31]
	v_pk_mul_f32 v[12:13], v[12:13], v[32:33]
